# unit loop head P1/P8/P3: first K-tile ds_reads hoisted above next-unit coordinate arithmetic; entry also touches kernarg line 0x100; stacked on v63
# baseline (speedup 1.0000x reference)
_Z6mk_fwd4Args:
	s_load_dwordx8 s[4:11], s[0:1], 0xc0
	s_load_dword s54, s[0:1], 0xf8
	s_load_dwordx4 s[68:71], s[0:1], 0xe0
	s_load_dwordx2 s[52:53], s[0:1], 0xf0
	s_load_dword s72, s[0:1], 0x0
	s_load_dword s73, s[0:1], 0x40
	s_load_dword s74, s[0:1], 0x80
	s_load_dword s75, s[0:1], 0x100
	s_mov_b32 s56, s2
	v_readfirstlane_b32 s2, v0
	s_mov_b32 s33, s56
	s_waitcnt lgkmcnt(0)
	v_writelane_b32 v254, s4, 0
	s_nop 1
	v_writelane_b32 v254, s5, 1
	v_writelane_b32 v254, s6, 2
	v_writelane_b32 v254, s7, 3
	v_writelane_b32 v254, s8, 4
	v_writelane_b32 v254, s9, 5
	v_writelane_b32 v254, s10, 6
	v_writelane_b32 v254, s11, 7
	s_add_u32 s4, s0, 0xf8
	s_addc_u32 s5, s1, 0
	v_writelane_b32 v254, s4, 8
	s_and_b32 s3, s54, 7
	s_cmp_lg_u32 s3, 0
	v_writelane_b32 v254, s5, 9
	s_cbranch_scc0 .LBB0_101
	v_cmp_gt_u32_e64 s[6:7], 64, v0
	s_and_saveexec_b64 s[4:5], s[6:7]

.LBB0_195:
	ds_read_b128 v[2:5], v145
	ds_read_b128 v[6:9], v145 offset:1024
	ds_read_b128 v[10:13], v145 offset:2048
	ds_read_b128 v[14:17], v145 offset:3072
	ds_read_b128 v[18:21], v146
	ds_read_b128 v[22:25], v146 offset:1024
	ds_read_b128 v[26:29], v146 offset:2048
	ds_read_b128 v[30:33], v146 offset:3072
	ds_read_b128 v[34:37], v147
	ds_read_b128 v[38:41], v147 offset:1024
	ds_read_b128 v[42:45], v147 offset:2048
	ds_read_b128 v[46:49], v147 offset:3072
	ds_read_b128 v[50:53], v147 offset:4096
	ds_read_b128 v[54:57], v147 offset:5120
	ds_read_b128 v[58:61], v147 offset:6144
	ds_read_b128 v[62:65], v147 offset:7168
	s_add_i32 s77, s53, 1
	v_readlane_b32 s1, v255, 5
	s_mul_hi_i32 s0, s77, s1
	s_mul_i32 s1, s77, s1
	v_readlane_b32 s2, v255, 6
	s_add_u32 s46, s1, s2
	s_addc_u32 s47, s0, s52
	v_cmp_gt_i64_e64 s[4:5], s[46:47], v[138:139]
	v_cmp_lt_i64_e64 s[0:1], s[46:47], v[136:137]
	s_and_b64 vcc, exec, s[4:5]
	s_cbranch_vccnz .LBB0_200
	s_cmpk_lt_i32 s46, 0x5d8
	s_mov_b64 s[48:49], -1
	s_cbranch_scc1 .LBB0_198
	s_add_i32 s2, s46, 0xfffffa28
	s_mul_hi_u32 s3, s2, 0xba2e8ba3
	s_lshr_b32 s3, s3, 4
	s_add_i32 s90, s3, 0x44
	s_mul_i32 s3, s3, 22
	s_sub_i32 s88, s2, s3
	s_mov_b64 s[48:49], 0
.LBB0_198:
	s_andn2_b64 vcc, exec, s[48:49]
	s_cbranch_vccnz .LBB0_200
	s_ashr_i32 s2, s46, 31
	s_lshr_b32 s2, s2, 29
	s_add_i32 s2, s46, s2
	s_ashr_i32 s3, s2, 3
	s_and_b32 s2, s2, -8
	s_sub_i32 s2, s46, s2
	s_cmp_lt_i32 s2, 0
	s_cselect_b32 s8, s16, 0xbb
	s_mul_i32 s2, s2, s8
	s_add_i32 s2, s2, s3
	s_mul_hi_i32 s3, s2, 0x2e8ba2e9
	s_lshr_b32 s8, s3, 31
	s_ashr_i32 s3, s3, 5
	s_add_i32 s3, s3, s8
	s_lshl_b32 s8, s3, 3
	s_sub_i32 s9, 0x44, s8
	s_min_u32 s9, s9, 8
	s_mulk_i32 s3, 0xb0
	s_sub_i32 s12, s2, s3
	v_cvt_f32_ubyte0_e32 v225, s9
	v_cvt_f32_i32_e32 v224, s12
	v_rcp_iflag_f32_e32 v226, v225
	s_ashr_i32 s2, s12, 30
	s_or_b32 s13, s2, 1
	v_mul_f32_e32 v226, v224, v226
	v_trunc_f32_e32 v226, v226
	v_fma_f32 v224, -v226, v225, v224
	v_cvt_i32_f32_e32 v226, v226
	v_cmp_ge_f32_e64 s[2:3], |v224|, v225
	s_and_b64 s[2:3], s[2:3], exec
	s_cselect_b32 s2, s13, 0
	v_readfirstlane_b32 s3, v226
	s_add_i32 s2, s3, s2
	s_sext_i32_i16 s88, s2
	s_mul_i32 s2, s2, s9
	s_sub_i32 s2, s12, s2
	s_sext_i32_i16 s2, s2
	s_add_i32 s90, s8, s2
.LBB0_200:
	s_add_u32 s46, s6, 0x200
	s_addc_u32 s47, s7, 0
	s_ashr_i32 s91, s90, 31
	s_lshl_b64 s[2:3], s[90:91], 19
	v_readlane_b32 s8, v254, 62
	v_readlane_b32 s9, v254, 63
	s_add_u32 s94, s8, s2
	s_addc_u32 s95, s9, s3
	s_and_b64 s[2:3], s[0:1], exec
	s_cselect_b32 s48, s95, s25
	s_cselect_b32 s49, s94, s24
	s_ashr_i32 s89, s88, 31
	s_lshl_b64 s[2:3], s[88:89], 19
	s_add_u32 s92, s68, s2
	s_addc_u32 s93, s69, s3
	s_and_b64 s[2:3], s[0:1], exec
	s_cselect_b32 s89, s93, s7
	s_cselect_b32 s91, s92, s6
	v_lshl_add_u64 v[140:141], s[24:25], 0, v[130:131]
	s_add_i32 vcc_lo, s11, 0xc000
	v_lshl_add_u64 v[66:67], v[140:141], 0, s[42:43]
	s_mov_b32 m0, vcc_lo
	s_add_i32 vcc_hi, s11, 0xe000
	global_load_lds_dwordx4 v[66:67], off
	v_lshl_add_u64 v[66:67], v[140:141], 0, s[44:45]
	s_mov_b32 m0, vcc_hi
	s_nop 0
	global_load_lds_dwordx4 v[66:67], off
	s_waitcnt vmcnt(8)
	s_waitcnt lgkmcnt(0)
	s_waitcnt lgkmcnt(0)
	v_mfma_f32_16x16x32_bf16 v[86:89], v[10:13], v[50:53], 0
	v_mfma_f32_16x16x32_bf16 v[90:93], v[14:17], v[54:57], v[86:89]
	s_barrier
	s_setprio 1
	v_mfma_f32_16x16x32_bf16 v[86:89], v[2:5], v[58:61], 0
	v_mfma_f32_16x16x32_bf16 v[66:69], v[2:5], v[34:37], 0
	v_mfma_f32_16x16x32_bf16 v[70:73], v[10:13], v[34:37], 0
	v_mfma_f32_16x16x32_bf16 v[74:77], v[2:5], v[42:45], 0
	v_mfma_f32_16x16x32_bf16 v[78:81], v[10:13], v[42:45], 0
	v_mfma_f32_16x16x32_bf16 v[82:85], v[2:5], v[50:53], 0
	v_mfma_f32_16x16x32_bf16 v[94:97], v[6:9], v[62:65], v[86:89]
	v_mfma_f32_16x16x32_bf16 v[86:89], v[10:13], v[58:61], 0
	v_mfma_f32_16x16x32_bf16 v[66:69], v[6:9], v[38:41], v[66:69]
	v_mfma_f32_16x16x32_bf16 v[70:73], v[14:17], v[38:41], v[70:73]
	v_mfma_f32_16x16x32_bf16 v[74:77], v[6:9], v[46:49], v[74:77]
	v_mfma_f32_16x16x32_bf16 v[78:81], v[14:17], v[46:49], v[78:81]
	v_mfma_f32_16x16x32_bf16 v[82:85], v[6:9], v[54:57], v[82:85]
	v_mfma_f32_16x16x32_bf16 v[106:109], v[14:17], v[62:65], v[86:89]
	s_setprio 0
	s_setprio 1
	v_mfma_f32_16x16x32_bf16 v[86:89], v[18:21], v[34:37], 0
	v_mfma_f32_16x16x32_bf16 v[34:37], v[26:29], v[34:37], 0
	v_mfma_f32_16x16x32_bf16 v[110:113], v[22:25], v[38:41], v[86:89]
	v_mfma_f32_16x16x32_bf16 v[34:37], v[30:33], v[38:41], v[34:37]
	v_mfma_f32_16x16x32_bf16 v[38:41], v[18:21], v[42:45], 0
	v_mfma_f32_16x16x32_bf16 v[42:45], v[26:29], v[42:45], 0
	v_mfma_f32_16x16x32_bf16 v[38:41], v[22:25], v[46:49], v[38:41]
	v_mfma_f32_16x16x32_bf16 v[42:45], v[30:33], v[46:49], v[42:45]
	v_mfma_f32_16x16x32_bf16 v[46:49], v[18:21], v[50:53], 0
	v_mfma_f32_16x16x32_bf16 v[50:53], v[26:29], v[50:53], 0
	v_mfma_f32_16x16x32_bf16 v[46:49], v[22:25], v[54:57], v[46:49]
	v_mfma_f32_16x16x32_bf16 v[50:53], v[30:33], v[54:57], v[50:53]
	v_mfma_f32_16x16x32_bf16 v[54:57], v[18:21], v[58:61], 0
	v_mfma_f32_16x16x32_bf16 v[58:61], v[26:29], v[58:61], 0
	v_mfma_f32_16x16x32_bf16 v[54:57], v[22:25], v[62:65], v[54:57]
	v_mfma_f32_16x16x32_bf16 v[58:61], v[30:33], v[62:65], v[58:61]
	s_setprio 0
	s_barrier
	v_lshl_add_u64 v[184:185], s[6:7], 0, v[132:133]
	s_add_i32 s8, s96, s51
	v_lshl_add_u64 v[150:151], v[184:185], 0, s[64:65]
	s_mov_b32 m0, s8
	s_add_i32 s9, s8, 0x2000
	ds_read_b128 v[62:65], v147 offset:16384
	ds_read_b128 v[86:89], v147 offset:17408
	ds_read_b128 v[98:101], v147 offset:18432
	ds_read_b128 v[102:105], v147 offset:19456
	ds_read_b128 v[114:117], v147 offset:20480
	ds_read_b128 v[118:121], v147 offset:21504
	ds_read_b128 v[122:125], v147 offset:22528
	ds_read_b128 v[126:129], v147 offset:23552
	global_load_lds_dwordx4 v[150:151], off
	v_lshl_add_u64 v[150:151], v[184:185], 0, s[66:67]
	s_mov_b32 m0, s9
	s_add_i32 s33, s97, s51
	global_load_lds_dwordx4 v[150:151], off
	v_lshl_add_u64 v[150:151], v[184:185], 0, s[72:73]
	s_mov_b32 m0, s33
	s_add_i32 s2, s33, 0x2000
	global_load_lds_dwordx4 v[150:151], off
	v_lshl_add_u64 v[150:151], v[184:185], 0, s[74:75]
	s_mov_b32 m0, s2
	s_nop 0
	global_load_lds_dwordx4 v[150:151], off
	v_lshl_add_u64 v[150:151], v[140:141], 0, s[64:65]
	s_mov_b32 m0, s11
	s_nop 0
	global_load_lds_dwordx4 v[150:151], off
	v_lshl_add_u64 v[150:151], v[140:141], 0, s[66:67]
	s_mov_b32 m0, s54
	s_nop 0
	global_load_lds_dwordx4 v[150:151], off
	s_waitcnt vmcnt(8)
	s_waitcnt lgkmcnt(0)
	s_waitcnt lgkmcnt(0)
	v_mfma_f32_16x16x32_bf16 v[150:153], v[2:5], v[62:65], 0
	v_mfma_f32_16x16x32_bf16 v[160:163], v[2:5], v[98:101], 0
	s_barrier
	s_setprio 1
	v_mfma_f32_16x16x32_bf16 v[168:171], v[2:5], v[114:117], 0
	v_mfma_f32_16x16x32_bf16 v[2:5], v[2:5], v[122:125], 0
	v_mfma_f32_16x16x32_bf16 v[152:155], v[6:9], v[86:89], v[150:153]
	v_mfma_f32_16x16x32_bf16 v[160:163], v[6:9], v[102:105], v[160:163]
	v_mfma_f32_16x16x32_bf16 v[168:171], v[6:9], v[118:121], v[168:171]
	v_mfma_f32_16x16x32_bf16 v[2:5], v[6:9], v[126:129], v[2:5]
	v_mfma_f32_16x16x32_bf16 v[6:9], v[10:13], v[122:125], 0
	v_mfma_f32_16x16x32_bf16 v[156:159], v[10:13], v[62:65], 0
	v_mfma_f32_16x16x32_bf16 v[164:167], v[10:13], v[98:101], 0
	v_mfma_f32_16x16x32_bf16 v[172:175], v[10:13], v[114:117], 0
	v_mfma_f32_16x16x32_bf16 v[10:13], v[14:17], v[126:129], v[6:9]
	v_mfma_f32_16x16x32_bf16 v[156:159], v[14:17], v[86:89], v[156:159]
	v_mfma_f32_16x16x32_bf16 v[164:167], v[14:17], v[102:105], v[164:167]
	v_mfma_f32_16x16x32_bf16 v[172:175], v[14:17], v[118:121], v[172:175]
	s_setprio 0
	s_setprio 1
	v_mfma_f32_16x16x32_bf16 v[6:9], v[18:21], v[62:65], 0
	v_mfma_f32_16x16x32_bf16 v[14:17], v[22:25], v[86:89], v[6:9]
	v_mfma_f32_16x16x32_bf16 v[6:9], v[26:29], v[62:65], 0
	v_mfma_f32_16x16x32_bf16 v[176:179], v[30:33], v[86:89], v[6:9]
	v_mfma_f32_16x16x32_bf16 v[6:9], v[18:21], v[98:101], 0
	v_mfma_f32_16x16x32_bf16 v[180:183], v[22:25], v[102:105], v[6:9]
	v_mfma_f32_16x16x32_bf16 v[6:9], v[26:29], v[98:101], 0
	v_mfma_f32_16x16x32_bf16 v[188:191], v[30:33], v[102:105], v[6:9]
	v_mfma_f32_16x16x32_bf16 v[6:9], v[18:21], v[114:117], 0
	v_mfma_f32_16x16x32_bf16 v[192:195], v[22:25], v[118:121], v[6:9]
	v_mfma_f32_16x16x32_bf16 v[6:9], v[26:29], v[114:117], 0
	v_mfma_f32_16x16x32_bf16 v[196:199], v[30:33], v[118:121], v[6:9]
	v_mfma_f32_16x16x32_bf16 v[6:9], v[18:21], v[122:125], 0
	v_mfma_f32_16x16x32_bf16 v[200:203], v[22:25], v[126:129], v[6:9]
	v_mfma_f32_16x16x32_bf16 v[6:9], v[26:29], v[122:125], 0
	v_mfma_f32_16x16x32_bf16 v[204:207], v[30:33], v[126:129], v[6:9]
	s_setprio 0
	s_barrier
	s_add_i32 s3, 0, 0x18000
	s_add_i32 s35, 0, 0x1c000
	v_add_u32_e32 v149, s3, v144
	v_add_u32_e32 v150, s35, v144
	s_nop 0
	ds_read_b128 v[6:9], v149
	ds_read_b128 v[26:29], v149 offset:1024
	ds_read_b128 v[30:33], v149 offset:2048
	ds_read_b128 v[208:211], v149 offset:3072
	ds_read_b128 v[212:215], v150
	ds_read_b128 v[216:219], v150 offset:1024
	ds_read_b128 v[220:223], v150 offset:2048
	ds_read_b128 v[224:227], v150 offset:3072
	s_mov_b32 m0, s55
	v_lshl_add_u64 v[62:63], v[140:141], 0, s[72:73]
	ds_read_b128 v[18:21], v147 offset:32768
	ds_read_b128 v[22:25], v147 offset:33792
	ds_read_b128 v[228:231], v147 offset:34816
	ds_read_b128 v[232:235], v147 offset:35840
	ds_read_b128 v[236:239], v147 offset:36864
	ds_read_b128 v[240:243], v147 offset:37888
	ds_read_b128 v[244:247], v147 offset:38912
	ds_read_b128 v[248:251], v147 offset:39936
	global_load_lds_dwordx4 v[62:63], off
	v_lshl_add_u64 v[62:63], v[140:141], 0, s[74:75]
	s_mov_b32 m0, s56
	s_nop 0
	global_load_lds_dwordx4 v[62:63], off
	s_waitcnt vmcnt(8)
	s_waitcnt lgkmcnt(0)
	s_waitcnt lgkmcnt(0)
	v_mfma_f32_16x16x32_bf16 v[62:65], v[6:9], v[18:21], v[66:69]
	v_mfma_f32_16x16x32_bf16 v[118:121], v[26:29], v[22:25], v[62:65]
	s_barrier
	s_setprio 1
	v_mfma_f32_16x16x32_bf16 v[62:65], v[30:33], v[18:21], v[70:73]
	v_mfma_f32_16x16x32_bf16 v[114:117], v[208:211], v[22:25], v[62:65]
	v_mfma_f32_16x16x32_bf16 v[62:65], v[6:9], v[228:231], v[74:77]
	v_mfma_f32_16x16x32_bf16 v[102:105], v[26:29], v[232:235], v[62:65]
	v_mfma_f32_16x16x32_bf16 v[62:65], v[30:33], v[228:231], v[78:81]
	v_mfma_f32_16x16x32_bf16 v[98:101], v[208:211], v[232:235], v[62:65]
	v_mfma_f32_16x16x32_bf16 v[62:65], v[6:9], v[236:239], v[82:85]
	v_mfma_f32_16x16x32_bf16 v[86:89], v[26:29], v[240:243], v[62:65]
	v_mfma_f32_16x16x32_bf16 v[62:65], v[30:33], v[236:239], v[90:93]
	v_mfma_f32_16x16x32_bf16 v[82:85], v[208:211], v[240:243], v[62:65]
	v_mfma_f32_16x16x32_bf16 v[62:65], v[6:9], v[244:247], v[94:97]
	v_mfma_f32_16x16x32_bf16 v[70:73], v[26:29], v[248:251], v[62:65]
	v_mfma_f32_16x16x32_bf16 v[62:65], v[30:33], v[244:247], v[106:109]
	v_mfma_f32_16x16x32_bf16 v[62:65], v[208:211], v[248:251], v[62:65]
	s_setprio 0
	s_setprio 1
	v_mfma_f32_16x16x32_bf16 v[66:69], v[212:215], v[18:21], v[110:113]
	v_mfma_f32_16x16x32_bf16 v[18:21], v[220:223], v[18:21], v[34:37]
	v_mfma_f32_16x16x32_bf16 v[122:125], v[224:227], v[22:25], v[18:21]
	v_mfma_f32_16x16x32_bf16 v[18:21], v[212:215], v[228:231], v[38:41]
	v_mfma_f32_16x16x32_bf16 v[110:113], v[216:219], v[232:235], v[18:21]
	v_mfma_f32_16x16x32_bf16 v[18:21], v[220:223], v[228:231], v[42:45]
	v_mfma_f32_16x16x32_bf16 v[106:109], v[224:227], v[232:235], v[18:21]
	v_mfma_f32_16x16x32_bf16 v[18:21], v[212:215], v[236:239], v[46:49]
	v_mfma_f32_16x16x32_bf16 v[94:97], v[216:219], v[240:243], v[18:21]
	v_mfma_f32_16x16x32_bf16 v[18:21], v[220:223], v[236:239], v[50:53]
	v_mfma_f32_16x16x32_bf16 v[90:93], v[224:227], v[240:243], v[18:21]
	v_mfma_f32_16x16x32_bf16 v[18:21], v[212:215], v[244:247], v[54:57]
	v_mfma_f32_16x16x32_bf16 v[78:81], v[216:219], v[248:251], v[18:21]
	v_mfma_f32_16x16x32_bf16 v[18:21], v[220:223], v[244:247], v[58:61]
	v_mfma_f32_16x16x32_bf16 v[126:129], v[216:219], v[22:25], v[66:69]
	v_mfma_f32_16x16x32_bf16 v[74:77], v[224:227], v[248:251], v[18:21]
	s_setprio 0
	s_barrier
	s_add_i32 s3, s3, s51
	s_nop 2
	v_lshl_add_u64 v[18:19], v[184:185], 0, s[78:79]
	s_mov_b32 m0, s3
	s_add_i32 s34, s3, 0x2000
	ds_read_b128 v[42:45], v147 offset:49152
	ds_read_b128 v[46:49], v147 offset:50176
	ds_read_b128 v[228:231], v147 offset:51200
	ds_read_b128 v[232:235], v147 offset:52224
	ds_read_b128 v[236:239], v147 offset:53248
	ds_read_b128 v[240:243], v147 offset:54272
	ds_read_b128 v[244:247], v147 offset:55296
	ds_read_b128 v[248:251], v147 offset:56320
	global_load_lds_dwordx4 v[18:19], off
	v_lshl_add_u64 v[18:19], v[184:185], 0, s[82:83]
	s_mov_b32 m0, s34
	s_add_i32 s35, s35, s51
	global_load_lds_dwordx4 v[18:19], off
	v_lshl_add_u64 v[18:19], v[184:185], 0, s[84:85]
	s_mov_b32 m0, s35
	s_add_i32 s36, s35, 0x2000
	global_load_lds_dwordx4 v[18:19], off
	v_lshl_add_u64 v[18:19], v[184:185], 0, s[86:87]
	s_mov_b32 m0, s36
	s_nop 0
	global_load_lds_dwordx4 v[18:19], off
	v_lshl_add_u64 v[18:19], v[140:141], 0, s[78:79]
	s_mov_b32 m0, s57
	s_nop 0
	global_load_lds_dwordx4 v[18:19], off
	v_lshl_add_u64 v[18:19], v[140:141], 0, s[82:83]
	s_mov_b32 m0, s58
	s_nop 0
	global_load_lds_dwordx4 v[18:19], off
	s_waitcnt vmcnt(8)
	s_waitcnt lgkmcnt(0)
	s_waitcnt lgkmcnt(0)
	v_mfma_f32_16x16x32_bf16 v[18:21], v[6:9], v[42:45], v[152:155]
	v_mfma_f32_16x16x32_bf16 v[54:57], v[26:29], v[46:49], v[18:21]
	s_barrier
	s_setprio 1
	v_mfma_f32_16x16x32_bf16 v[18:21], v[30:33], v[42:45], v[156:159]
	v_mfma_f32_16x16x32_bf16 v[50:53], v[208:211], v[46:49], v[18:21]
	v_mfma_f32_16x16x32_bf16 v[18:21], v[6:9], v[228:231], v[160:163]
	v_mfma_f32_16x16x32_bf16 v[38:41], v[26:29], v[232:235], v[18:21]
	v_mfma_f32_16x16x32_bf16 v[18:21], v[30:33], v[228:231], v[164:167]
	v_mfma_f32_16x16x32_bf16 v[34:37], v[208:211], v[232:235], v[18:21]
	v_mfma_f32_16x16x32_bf16 v[18:21], v[6:9], v[236:239], v[168:171]
	v_mfma_f32_16x16x32_bf16 v[2:5], v[6:9], v[244:247], v[2:5]
	v_mfma_f32_16x16x32_bf16 v[22:25], v[26:29], v[240:243], v[18:21]
	v_mfma_f32_16x16x32_bf16 v[18:21], v[30:33], v[236:239], v[172:175]
	v_mfma_f32_16x16x32_bf16 v[6:9], v[26:29], v[248:251], v[2:5]
	v_mfma_f32_16x16x32_bf16 v[2:5], v[30:33], v[244:247], v[10:13]
	v_mfma_f32_16x16x32_bf16 v[18:21], v[208:211], v[240:243], v[18:21]
	v_mfma_f32_16x16x32_bf16 v[2:5], v[208:211], v[248:251], v[2:5]
	s_setprio 0
	s_setprio 1
	v_mfma_f32_16x16x32_bf16 v[10:13], v[212:215], v[42:45], v[14:17]
	v_mfma_f32_16x16x32_bf16 v[66:69], v[216:219], v[46:49], v[10:13]
	v_mfma_f32_16x16x32_bf16 v[10:13], v[220:223], v[42:45], v[176:179]
	v_mfma_f32_16x16x32_bf16 v[58:61], v[224:227], v[46:49], v[10:13]
	v_mfma_f32_16x16x32_bf16 v[10:13], v[212:215], v[228:231], v[180:183]
	v_mfma_f32_16x16x32_bf16 v[46:49], v[216:219], v[232:235], v[10:13]
	v_mfma_f32_16x16x32_bf16 v[10:13], v[220:223], v[228:231], v[188:191]
	v_mfma_f32_16x16x32_bf16 v[42:45], v[224:227], v[232:235], v[10:13]
	v_mfma_f32_16x16x32_bf16 v[10:13], v[212:215], v[236:239], v[192:195]
	v_mfma_f32_16x16x32_bf16 v[30:33], v[216:219], v[240:243], v[10:13]
	v_mfma_f32_16x16x32_bf16 v[10:13], v[220:223], v[236:239], v[196:199]
	v_mfma_f32_16x16x32_bf16 v[26:29], v[224:227], v[240:243], v[10:13]
	v_mfma_f32_16x16x32_bf16 v[10:13], v[212:215], v[244:247], v[200:203]
	v_mfma_f32_16x16x32_bf16 v[14:17], v[216:219], v[248:251], v[10:13]
	v_mfma_f32_16x16x32_bf16 v[10:13], v[220:223], v[244:247], v[204:207]
	v_mfma_f32_16x16x32_bf16 v[10:13], v[224:227], v[248:251], v[10:13]
	s_setprio 0
	s_barrier
	v_lshl_add_u64 v[140:141], s[24:25], 0, v[134:135]
	s_mov_b32 s37, 0
	s_mov_b64 s[6:7], 0

.LBB0_707:
	ds_read_b128 v[2:5], v177
	ds_read_b128 v[6:9], v177 offset:1024
	ds_read_b128 v[10:13], v177 offset:2048
	ds_read_b128 v[14:17], v177 offset:3072
	ds_read_b128 v[18:21], v178
	ds_read_b128 v[22:25], v178 offset:1024
	ds_read_b128 v[26:29], v178 offset:2048
	ds_read_b128 v[30:33], v178 offset:3072
	ds_read_b128 v[34:37], v179
	ds_read_b128 v[38:41], v179 offset:1024
	ds_read_b128 v[42:45], v179 offset:2048
	ds_read_b128 v[46:49], v179 offset:3072
	ds_read_b128 v[50:53], v179 offset:4096
	ds_read_b128 v[54:57], v179 offset:5120
	ds_read_b128 v[58:61], v179 offset:6144
	ds_read_b128 v[62:65], v179 offset:7168
	s_add_i32 s57, s25, 1
	s_mul_i32 s2, s57, s54
	v_readlane_b32 s10, v255, 6
	s_add_i32 s2, s2, s10
	s_cmpk_gt_i32 s2, 0x32f
	s_mov_b64 s[46:47], -1
	s_cbranch_scc0 .LBB0_710
	s_mov_b64 s[46:47], 0
	s_cmpk_gt_u32 s2, 0x65f
	s_mov_b64 s[10:11], 0
	s_cbranch_scc1 .LBB0_710
	s_and_b32 s10, s2, 7
	s_add_i32 s11, s2, 0xfcd0
	s_bfe_u32 s11, s11, 0xd0003
	s_mulk_i32 s10, 0x66
	s_add_i32 s11, s11, s10
	s_and_b32 s10, s11, 0xffff
	s_mul_i32 s10, s10, 0xaaab
	s_lshr_b32 s10, s10, 22
	s_lshl_b32 s12, s10, 3
	s_sub_i32 s13, 0x44, s12
	s_mulk_i32 s10, 0x60
	s_min_u32 s13, s13, 8
	s_sub_i32 s14, s11, s10
	s_and_b32 s10, s14, 0xffff
	v_cvt_f32_ubyte0_e32 v225, s13
	v_cvt_f32_u32_e32 v224, s10
	v_rcp_iflag_f32_e32 v226, v225
	s_mov_b32 s33, s16
	v_mul_f32_e32 v226, v224, v226
	v_trunc_f32_e32 v226, v226
	v_fma_f32 v224, -v226, v225, v224
	v_cvt_u32_f32_e32 v226, v226
	v_cmp_ge_f32_e64 s[10:11], |v224|, v225
	s_cmp_lg_u64 s[10:11], 0
	v_readfirstlane_b32 s15, v226
	s_addc_u32 s16, s15, 0
	s_mul_i32 s16, s16, s13
	s_sub_i32 s13, s14, s16
	s_and_b32 s13, s13, 0xff
	s_add_i32 s44, s13, s12
	s_cmp_lg_u64 s[10:11], 0
	s_addc_u32 s10, s15, 12
	s_mov_b32 s16, s33
	s_and_b32 s62, s10, 0xff
	s_mov_b64 s[10:11], -1
.LBB0_710:
	s_andn2_b64 vcc, exec, s[46:47]
	s_cbranch_vccnz .LBB0_712
	s_ashr_i32 s10, s2, 31
	s_lshr_b32 s10, s10, 29
	s_add_i32 s10, s2, s10
	s_ashr_i32 s11, s10, 3
	s_and_b32 s10, s10, -8
	s_sub_i32 s2, s2, s10
	s_cmp_lt_i32 s2, 0
	s_movk_i32 s10, 0x67
	s_cselect_b32 s10, s10, 0x66
	s_mul_i32 s2, s2, s10
	s_add_i32 s2, s2, s11
	s_mul_hi_i32 s10, s2, 0x2aaaaaab
	s_lshr_b32 s11, s10, 31
	s_ashr_i32 s10, s10, 4
	s_add_i32 s10, s10, s11
	s_lshl_b32 s12, s10, 3
	s_sub_i32 s11, 0x44, s12
	s_min_u32 s13, s11, 8
	s_mulk_i32 s10, 0x60
	s_sub_i32 s2, s2, s10
	v_cvt_f32_ubyte0_e32 v225, s13
	v_cvt_f32_i32_e32 v224, s2
	v_rcp_iflag_f32_e32 v226, v225
	s_ashr_i32 s10, s2, 30
	s_or_b32 s14, s10, 1
	v_mul_f32_e32 v226, v224, v226
	v_trunc_f32_e32 v226, v226
	v_fma_f32 v224, -v226, v225, v224
	v_cvt_i32_f32_e32 v226, v226
	v_cmp_ge_f32_e64 s[10:11], |v224|, v225
	s_and_b64 s[10:11], s[10:11], exec
	s_cselect_b32 s10, s14, 0
	v_readfirstlane_b32 s11, v226
	s_add_i32 s10, s11, s10
	s_sext_i32_i8 s62, s10
	s_mul_i32 s10, s10, s13
	s_sub_i32 s2, s2, s10
	s_sext_i32_i8 s2, s2
	s_add_i32 s44, s12, s2
	s_mov_b64 s[10:11], -1
.LBB0_712:
	s_ashr_i32 s45, s44, 31
	s_xor_b64 s[46:47], s[10:11], -1
	s_lshl_b64 s[12:13], s[44:45], 19
	v_readlane_b32 s14, v254, 62
	v_readlane_b32 s15, v254, 63
	s_add_u32 s80, s14, s12
	s_addc_u32 s81, s15, s13
	s_and_b64 s[12:13], s[10:11], exec
	s_cselect_b32 s41, s81, s49
	s_cselect_b32 s45, s80, s48
	s_ashr_i32 s63, s62, 31
	s_lshl_b64 s[12:13], s[62:63], 19
	v_readlane_b32 s14, v255, 17
	v_readlane_b32 s15, v255, 18
	s_add_u32 s66, s14, s12
	s_addc_u32 s67, s15, s13
	s_and_b64 s[12:13], s[10:11], exec
	s_cselect_b32 s58, s67, s65
	s_cselect_b32 s59, s66, s64
	v_lshl_add_u64 v[160:161], s[48:49], 0, v[162:163]
	s_add_i32 s60, s92, 0xc000
	v_lshl_add_u64 v[66:67], v[160:161], 0, s[72:73]
	s_mov_b32 m0, s60
	s_add_i32 s61, s92, 0xe000
	global_load_lds_dwordx4 v[66:67], off
	v_lshl_add_u64 v[66:67], v[160:161], 0, s[78:79]
	s_mov_b32 m0, s61
	s_nop 0
	global_load_lds_dwordx4 v[66:67], off
	s_waitcnt vmcnt(8)
	s_waitcnt lgkmcnt(0)
	s_waitcnt lgkmcnt(0)
	v_mfma_f32_16x16x32_bf16 v[86:89], v[10:13], v[50:53], 0
	v_mfma_f32_16x16x32_bf16 v[90:93], v[14:17], v[54:57], v[86:89]
	s_barrier
	s_setprio 1
	v_mfma_f32_16x16x32_bf16 v[86:89], v[2:5], v[58:61], 0
	v_mfma_f32_16x16x32_bf16 v[66:69], v[2:5], v[34:37], 0
	v_mfma_f32_16x16x32_bf16 v[70:73], v[10:13], v[34:37], 0
	v_mfma_f32_16x16x32_bf16 v[74:77], v[2:5], v[42:45], 0
	v_mfma_f32_16x16x32_bf16 v[78:81], v[10:13], v[42:45], 0
	v_mfma_f32_16x16x32_bf16 v[82:85], v[2:5], v[50:53], 0
	v_mfma_f32_16x16x32_bf16 v[94:97], v[6:9], v[62:65], v[86:89]
	v_mfma_f32_16x16x32_bf16 v[86:89], v[10:13], v[58:61], 0
	v_mfma_f32_16x16x32_bf16 v[66:69], v[6:9], v[38:41], v[66:69]
	v_mfma_f32_16x16x32_bf16 v[70:73], v[14:17], v[38:41], v[70:73]
	v_mfma_f32_16x16x32_bf16 v[74:77], v[6:9], v[46:49], v[74:77]
	v_mfma_f32_16x16x32_bf16 v[78:81], v[14:17], v[46:49], v[78:81]
	v_mfma_f32_16x16x32_bf16 v[82:85], v[6:9], v[54:57], v[82:85]
	v_mfma_f32_16x16x32_bf16 v[106:109], v[14:17], v[62:65], v[86:89]
	s_setprio 0
	s_setprio 1
	v_mfma_f32_16x16x32_bf16 v[86:89], v[18:21], v[34:37], 0
	v_mfma_f32_16x16x32_bf16 v[34:37], v[26:29], v[34:37], 0
	v_mfma_f32_16x16x32_bf16 v[110:113], v[22:25], v[38:41], v[86:89]
	v_mfma_f32_16x16x32_bf16 v[34:37], v[30:33], v[38:41], v[34:37]
	v_mfma_f32_16x16x32_bf16 v[38:41], v[18:21], v[42:45], 0
	v_mfma_f32_16x16x32_bf16 v[42:45], v[26:29], v[42:45], 0
	v_mfma_f32_16x16x32_bf16 v[38:41], v[22:25], v[46:49], v[38:41]
	v_mfma_f32_16x16x32_bf16 v[42:45], v[30:33], v[46:49], v[42:45]
	v_mfma_f32_16x16x32_bf16 v[46:49], v[18:21], v[50:53], 0
	v_mfma_f32_16x16x32_bf16 v[132:135], v[22:25], v[54:57], v[46:49]
	v_mfma_f32_16x16x32_bf16 v[46:49], v[26:29], v[50:53], 0
	v_mfma_f32_16x16x32_bf16 v[50:53], v[30:33], v[54:57], v[46:49]
	v_mfma_f32_16x16x32_bf16 v[46:49], v[18:21], v[58:61], 0
	v_mfma_f32_16x16x32_bf16 v[136:139], v[22:25], v[62:65], v[46:49]
	v_mfma_f32_16x16x32_bf16 v[46:49], v[26:29], v[58:61], 0
	v_mfma_f32_16x16x32_bf16 v[58:61], v[30:33], v[62:65], v[46:49]
	s_setprio 0
	s_barrier
	v_lshl_add_u64 v[252:253], s[64:65], 0, v[164:165]
	s_add_i32 s63, s52, s51
	v_lshl_add_u64 v[122:123], v[252:253], 0, s[26:27]
	s_mov_b32 m0, s63
	s_add_i32 vcc_lo, s63, 0x2000
	ds_read_b128 v[46:49], v179 offset:16384
	ds_read_b128 v[54:57], v179 offset:17408
	ds_read_b128 v[62:65], v179 offset:18432
	ds_read_b128 v[86:89], v179 offset:19456
	ds_read_b128 v[98:101], v179 offset:20480
	ds_read_b128 v[102:105], v179 offset:21504
	ds_read_b128 v[114:117], v179 offset:22528
	ds_read_b128 v[118:121], v179 offset:23552
	global_load_lds_dwordx4 v[122:123], off
	v_lshl_add_u64 v[122:123], v[252:253], 0, s[28:29]
	s_mov_b32 m0, vcc_lo
	s_add_i32 vcc_hi, s53, s51
	global_load_lds_dwordx4 v[122:123], off
	v_lshl_add_u64 v[122:123], v[252:253], 0, s[30:31]
	s_mov_b32 m0, vcc_hi
	s_add_i32 s54, vcc_hi, 0x2000
	global_load_lds_dwordx4 v[122:123], off
	v_lshl_add_u64 v[122:123], v[252:253], 0, s[74:75]
	s_mov_b32 m0, s54
	s_nop 0
	global_load_lds_dwordx4 v[122:123], off
	v_lshl_add_u64 v[122:123], v[160:161], 0, s[26:27]
	s_mov_b32 m0, s92
	s_nop 0
	global_load_lds_dwordx4 v[122:123], off
	v_lshl_add_u64 v[122:123], v[160:161], 0, s[28:29]
	s_mov_b32 m0, s93
	s_nop 0
	global_load_lds_dwordx4 v[122:123], off
	s_waitcnt vmcnt(8)
	s_waitcnt lgkmcnt(0)
	s_waitcnt lgkmcnt(0)
	v_mfma_f32_16x16x32_bf16 v[122:125], v[2:5], v[46:49], 0
	v_mfma_f32_16x16x32_bf16 v[140:143], v[6:9], v[54:57], v[122:125]
	s_barrier
	s_setprio 1
	v_mfma_f32_16x16x32_bf16 v[122:125], v[10:13], v[46:49], 0
	v_mfma_f32_16x16x32_bf16 v[144:147], v[14:17], v[54:57], v[122:125]
	v_mfma_f32_16x16x32_bf16 v[122:125], v[2:5], v[62:65], 0
	v_mfma_f32_16x16x32_bf16 v[148:151], v[6:9], v[86:89], v[122:125]
	v_mfma_f32_16x16x32_bf16 v[122:125], v[10:13], v[62:65], 0
	v_mfma_f32_16x16x32_bf16 v[152:155], v[14:17], v[86:89], v[122:125]
	v_mfma_f32_16x16x32_bf16 v[122:125], v[2:5], v[98:101], 0
	v_mfma_f32_16x16x32_bf16 v[2:5], v[2:5], v[114:117], 0
	v_mfma_f32_16x16x32_bf16 v[156:159], v[6:9], v[102:105], v[122:125]
	v_mfma_f32_16x16x32_bf16 v[2:5], v[6:9], v[118:121], v[2:5]
	v_mfma_f32_16x16x32_bf16 v[6:9], v[10:13], v[114:117], 0
	v_mfma_f32_16x16x32_bf16 v[122:125], v[10:13], v[98:101], 0
	v_mfma_f32_16x16x32_bf16 v[10:13], v[14:17], v[118:121], v[6:9]
	v_mfma_f32_16x16x32_bf16 v[170:173], v[14:17], v[102:105], v[122:125]
	s_setprio 0
	s_setprio 1
	v_mfma_f32_16x16x32_bf16 v[6:9], v[18:21], v[46:49], 0
	v_mfma_f32_16x16x32_bf16 v[14:17], v[22:25], v[54:57], v[6:9]
	v_mfma_f32_16x16x32_bf16 v[6:9], v[26:29], v[46:49], 0
	v_mfma_f32_16x16x32_bf16 v[182:185], v[30:33], v[54:57], v[6:9]
	v_mfma_f32_16x16x32_bf16 v[6:9], v[18:21], v[62:65], 0
	v_mfma_f32_16x16x32_bf16 v[188:191], v[22:25], v[86:89], v[6:9]
	v_mfma_f32_16x16x32_bf16 v[6:9], v[26:29], v[62:65], 0
	v_mfma_f32_16x16x32_bf16 v[192:195], v[30:33], v[86:89], v[6:9]
	v_mfma_f32_16x16x32_bf16 v[6:9], v[18:21], v[98:101], 0
	v_mfma_f32_16x16x32_bf16 v[196:199], v[22:25], v[102:105], v[6:9]
	v_mfma_f32_16x16x32_bf16 v[6:9], v[26:29], v[98:101], 0
	v_mfma_f32_16x16x32_bf16 v[200:203], v[30:33], v[102:105], v[6:9]
	v_mfma_f32_16x16x32_bf16 v[6:9], v[18:21], v[114:117], 0
	v_mfma_f32_16x16x32_bf16 v[204:207], v[22:25], v[118:121], v[6:9]
	v_mfma_f32_16x16x32_bf16 v[6:9], v[26:29], v[114:117], 0
	v_mfma_f32_16x16x32_bf16 v[208:211], v[30:33], v[118:121], v[6:9]
	s_setprio 0
	s_barrier
	s_add_i32 s2, 0, 0x18000
	s_add_i32 s82, 0, 0x1c000
	v_add_u32_e32 v130, s2, v176
	v_add_u32_e32 v131, s82, v176
	s_nop 0
	ds_read_b128 v[6:9], v130
	ds_read_b128 v[26:29], v130 offset:1024
	ds_read_b128 v[30:33], v130 offset:2048
	ds_read_b128 v[212:215], v130 offset:3072
	ds_read_b128 v[216:219], v131
	ds_read_b128 v[220:223], v131 offset:1024
	ds_read_b128 v[224:227], v131 offset:2048
	ds_read_b128 v[228:231], v131 offset:3072
	s_mov_b32 m0, s0
	v_lshl_add_u64 v[46:47], v[160:161], 0, s[30:31]
	ds_read_b128 v[18:21], v179 offset:32768
	ds_read_b128 v[22:25], v179 offset:33792
	ds_read_b128 v[62:65], v179 offset:34816
	ds_read_b128 v[232:235], v179 offset:35840
	ds_read_b128 v[236:239], v179 offset:36864
	ds_read_b128 v[240:243], v179 offset:37888
	ds_read_b128 v[244:247], v179 offset:38912
	ds_read_b128 v[248:251], v179 offset:39936
	global_load_lds_dwordx4 v[46:47], off
	v_lshl_add_u64 v[46:47], v[160:161], 0, s[74:75]
	s_mov_b32 m0, s1
	s_nop 0
	global_load_lds_dwordx4 v[46:47], off
	s_waitcnt vmcnt(8)
	s_waitcnt lgkmcnt(0)
	s_waitcnt lgkmcnt(0)
	v_mfma_f32_16x16x32_bf16 v[46:49], v[6:9], v[18:21], v[66:69]
	v_mfma_f32_16x16x32_bf16 v[118:121], v[26:29], v[22:25], v[46:49]
	s_barrier
	s_setprio 1
	v_mfma_f32_16x16x32_bf16 v[46:49], v[30:33], v[18:21], v[70:73]
	v_mfma_f32_16x16x32_bf16 v[114:117], v[212:215], v[22:25], v[46:49]
	v_mfma_f32_16x16x32_bf16 v[46:49], v[6:9], v[62:65], v[74:77]
	v_mfma_f32_16x16x32_bf16 v[102:105], v[26:29], v[232:235], v[46:49]
	v_mfma_f32_16x16x32_bf16 v[46:49], v[30:33], v[62:65], v[78:81]
	v_mfma_f32_16x16x32_bf16 v[98:101], v[212:215], v[232:235], v[46:49]
	v_mfma_f32_16x16x32_bf16 v[46:49], v[6:9], v[236:239], v[82:85]
	v_mfma_f32_16x16x32_bf16 v[86:89], v[26:29], v[240:243], v[46:49]
	v_mfma_f32_16x16x32_bf16 v[46:49], v[30:33], v[236:239], v[90:93]
	v_mfma_f32_16x16x32_bf16 v[78:81], v[212:215], v[240:243], v[46:49]
	v_mfma_f32_16x16x32_bf16 v[46:49], v[6:9], v[244:247], v[94:97]
	v_mfma_f32_16x16x32_bf16 v[54:57], v[26:29], v[248:251], v[46:49]
	v_mfma_f32_16x16x32_bf16 v[46:49], v[30:33], v[244:247], v[106:109]
	v_mfma_f32_16x16x32_bf16 v[46:49], v[212:215], v[248:251], v[46:49]
	s_setprio 0
	s_setprio 1
	v_mfma_f32_16x16x32_bf16 v[66:69], v[216:219], v[18:21], v[110:113]
	v_mfma_f32_16x16x32_bf16 v[18:21], v[224:227], v[18:21], v[34:37]
	v_mfma_f32_16x16x32_bf16 v[122:125], v[228:231], v[22:25], v[18:21]
	v_mfma_f32_16x16x32_bf16 v[18:21], v[216:219], v[62:65], v[38:41]
	v_mfma_f32_16x16x32_bf16 v[110:113], v[220:223], v[232:235], v[18:21]
	v_mfma_f32_16x16x32_bf16 v[18:21], v[224:227], v[62:65], v[42:45]
	v_mfma_f32_16x16x32_bf16 v[106:109], v[228:231], v[232:235], v[18:21]
	v_mfma_f32_16x16x32_bf16 v[18:21], v[216:219], v[236:239], v[132:135]
	v_mfma_f32_16x16x32_bf16 v[94:97], v[220:223], v[240:243], v[18:21]
	v_mfma_f32_16x16x32_bf16 v[18:21], v[224:227], v[236:239], v[50:53]
	v_mfma_f32_16x16x32_bf16 v[90:93], v[228:231], v[240:243], v[18:21]
	v_mfma_f32_16x16x32_bf16 v[18:21], v[216:219], v[244:247], v[136:139]
	v_mfma_f32_16x16x32_bf16 v[126:129], v[220:223], v[22:25], v[66:69]
	v_mfma_f32_16x16x32_bf16 v[66:69], v[220:223], v[248:251], v[18:21]
	v_mfma_f32_16x16x32_bf16 v[18:21], v[224:227], v[244:247], v[58:61]
	v_mfma_f32_16x16x32_bf16 v[58:61], v[228:231], v[248:251], v[18:21]
	s_setprio 0
	s_barrier
	s_add_i32 s2, s2, s51
	s_nop 3
	v_lshl_add_u64 v[18:19], v[252:253], 0, s[38:39]
	s_mov_b32 m0, s2
	s_add_i32 s33, s2, 0x2000
	ds_read_b128 v[42:45], v179 offset:49152
	ds_read_b128 v[50:53], v179 offset:50176
	ds_read_b128 v[132:135], v179 offset:51200
	ds_read_b128 v[136:139], v179 offset:52224
	ds_read_b128 v[232:235], v179 offset:53248
	ds_read_b128 v[236:239], v179 offset:54272
	ds_read_b128 v[240:243], v179 offset:55296
	ds_read_b128 v[244:247], v179 offset:56320
	global_load_lds_dwordx4 v[18:19], off
	v_lshl_add_u64 v[18:19], v[252:253], 0, s[6:7]
	s_mov_b32 m0, s33
	s_mov_b64 s[12:13], 0x40180
	s_add_i32 s82, s82, s51
	global_load_lds_dwordx4 v[18:19], off
	v_lshl_add_u64 v[18:19], v[252:253], 0, s[12:13]
	s_mov_b32 m0, s82
	s_mov_b64 s[12:13], 0x60180
	s_add_i32 s50, s82, 0x2000
	global_load_lds_dwordx4 v[18:19], off
	v_lshl_add_u64 v[18:19], v[252:253], 0, s[12:13]
	s_mov_b32 m0, s50
	s_nop 0
	global_load_lds_dwordx4 v[18:19], off
	v_lshl_add_u64 v[18:19], v[160:161], 0, s[38:39]
	s_mov_b32 m0, s3
	s_nop 0
	global_load_lds_dwordx4 v[18:19], off
	v_lshl_add_u64 v[18:19], v[160:161], 0, s[6:7]
	s_mov_b32 m0, s76
	s_nop 0
	global_load_lds_dwordx4 v[18:19], off
	s_waitcnt vmcnt(8)
	s_waitcnt lgkmcnt(0)
	s_waitcnt lgkmcnt(0)
	v_mfma_f32_16x16x32_bf16 v[18:21], v[6:9], v[42:45], v[140:143]
	v_mfma_f32_16x16x32_bf16 v[70:73], v[26:29], v[50:53], v[18:21]
	s_barrier
	s_setprio 1
	v_mfma_f32_16x16x32_bf16 v[18:21], v[30:33], v[42:45], v[144:147]
	v_mfma_f32_16x16x32_bf16 v[62:65], v[212:215], v[50:53], v[18:21]
	v_mfma_f32_16x16x32_bf16 v[18:21], v[6:9], v[132:135], v[148:151]
	v_mfma_f32_16x16x32_bf16 v[38:41], v[26:29], v[136:139], v[18:21]
	v_mfma_f32_16x16x32_bf16 v[18:21], v[30:33], v[132:135], v[152:155]
	v_mfma_f32_16x16x32_bf16 v[34:37], v[212:215], v[136:139], v[18:21]
	v_mfma_f32_16x16x32_bf16 v[18:21], v[6:9], v[232:235], v[156:159]
	v_mfma_f32_16x16x32_bf16 v[2:5], v[6:9], v[240:243], v[2:5]
	v_mfma_f32_16x16x32_bf16 v[22:25], v[26:29], v[236:239], v[18:21]
	v_mfma_f32_16x16x32_bf16 v[18:21], v[30:33], v[232:235], v[170:173]
	v_mfma_f32_16x16x32_bf16 v[6:9], v[26:29], v[244:247], v[2:5]
	v_mfma_f32_16x16x32_bf16 v[2:5], v[30:33], v[240:243], v[10:13]
	v_mfma_f32_16x16x32_bf16 v[18:21], v[212:215], v[236:239], v[18:21]
	v_mfma_f32_16x16x32_bf16 v[2:5], v[212:215], v[244:247], v[2:5]
	s_setprio 0
	s_setprio 1
	v_mfma_f32_16x16x32_bf16 v[10:13], v[216:219], v[42:45], v[14:17]
	v_mfma_f32_16x16x32_bf16 v[82:85], v[220:223], v[50:53], v[10:13]
	v_mfma_f32_16x16x32_bf16 v[10:13], v[224:227], v[42:45], v[182:185]
	v_mfma_f32_16x16x32_bf16 v[74:77], v[228:231], v[50:53], v[10:13]
	v_mfma_f32_16x16x32_bf16 v[10:13], v[216:219], v[132:135], v[188:191]
	v_mfma_f32_16x16x32_bf16 v[50:53], v[220:223], v[136:139], v[10:13]
	v_mfma_f32_16x16x32_bf16 v[10:13], v[224:227], v[132:135], v[192:195]
	v_mfma_f32_16x16x32_bf16 v[42:45], v[228:231], v[136:139], v[10:13]
	v_mfma_f32_16x16x32_bf16 v[10:13], v[216:219], v[232:235], v[196:199]
	v_mfma_f32_16x16x32_bf16 v[30:33], v[220:223], v[236:239], v[10:13]
	v_mfma_f32_16x16x32_bf16 v[10:13], v[224:227], v[232:235], v[200:203]
	v_mfma_f32_16x16x32_bf16 v[26:29], v[228:231], v[236:239], v[10:13]
	v_mfma_f32_16x16x32_bf16 v[10:13], v[216:219], v[240:243], v[204:207]
	v_mfma_f32_16x16x32_bf16 v[14:17], v[220:223], v[244:247], v[10:13]
	v_mfma_f32_16x16x32_bf16 v[10:13], v[224:227], v[240:243], v[208:211]
	v_mfma_f32_16x16x32_bf16 v[10:13], v[228:231], v[244:247], v[10:13]
	s_setprio 0
	s_barrier
	s_add_u32 s48, s48, 0x40180
	s_addc_u32 s49, s49, 0
	s_add_u32 s36, s64, 0x200
	s_addc_u32 s37, s65, 0
	s_mov_b32 s64, 0

.LBB0_1712:
	ds_read_b128 v[2:5], v145
	ds_read_b128 v[6:9], v145 offset:1024
	ds_read_b128 v[10:13], v145 offset:2048
	ds_read_b128 v[14:17], v145 offset:3072
	ds_read_b128 v[18:21], v146
	ds_read_b128 v[22:25], v146 offset:1024
	ds_read_b128 v[26:29], v146 offset:2048
	ds_read_b128 v[30:33], v146 offset:3072
	ds_read_b128 v[34:37], v147
	ds_read_b128 v[38:41], v147 offset:1024
	ds_read_b128 v[42:45], v147 offset:2048
	ds_read_b128 v[46:49], v147 offset:3072
	ds_read_b128 v[50:53], v147 offset:4096
	ds_read_b128 v[54:57], v147 offset:5120
	ds_read_b128 v[58:61], v147 offset:6144
	ds_read_b128 v[62:65], v147 offset:7168
	s_add_i32 s92, s85, 1
	v_readlane_b32 s1, v255, 5
	s_mul_hi_i32 s0, s92, s1
	s_mul_i32 s1, s92, s1
	v_readlane_b32 s3, v255, 6
	s_add_u32 s50, s1, s3
	s_addc_u32 s51, s0, s53
	v_cmp_gt_i64_e64 s[4:5], s[50:51], v[138:139]
	v_cmp_lt_i64_e64 s[0:1], s[50:51], v[136:137]
	s_and_b64 vcc, exec, s[4:5]
	s_cbranch_vccnz .LBB0_1717
	s_cmpk_lt_i32 s50, 0x5d8
	s_mov_b64 s[74:75], -1
	s_cbranch_scc1 .LBB0_1715
	s_add_i32 s3, s50, 0xfffffa28
	s_mul_hi_u32 s12, s3, 0xba2e8ba3
	s_lshr_b32 s12, s12, 4
	s_add_i32 s72, s12, 0x44
	s_mul_i32 s12, s12, 22
	s_sub_i32 s66, s3, s12
	s_mov_b64 s[74:75], 0
.LBB0_1715:
	s_andn2_b64 vcc, exec, s[74:75]
	s_cbranch_vccnz .LBB0_1717
	s_ashr_i32 s3, s50, 31
	s_lshr_b32 s3, s3, 29
	s_add_i32 s3, s50, s3
	s_ashr_i32 s12, s3, 3
	s_and_b32 s3, s3, -8
	s_sub_i32 s3, s50, s3
	s_cmp_lt_i32 s3, 0
	s_cselect_b32 s13, s76, 0xbb
	s_mul_i32 s3, s3, s13
	s_add_i32 s3, s3, s12
	s_mul_hi_i32 s12, s3, 0x2e8ba2e9
	s_lshr_b32 s13, s12, 31
	s_ashr_i32 s12, s12, 5
	s_add_i32 s12, s12, s13
	s_lshl_b32 s18, s12, 3
	s_sub_i32 s13, 0x44, s18
	s_min_u32 s19, s13, 8
	s_mulk_i32 s12, 0xb0
	s_sub_i32 s3, s3, s12
	v_cvt_f32_ubyte0_e32 v225, s19
	v_cvt_f32_i32_e32 v224, s3
	v_rcp_iflag_f32_e32 v226, v225
	s_ashr_i32 s12, s3, 30
	s_or_b32 s20, s12, 1
	v_mul_f32_e32 v226, v224, v226
	v_trunc_f32_e32 v226, v226
	v_fma_f32 v224, -v226, v225, v224
	v_cvt_i32_f32_e32 v226, v226
	v_cmp_ge_f32_e64 s[12:13], |v224|, v225
	s_and_b64 s[12:13], s[12:13], exec
	s_cselect_b32 s12, s20, 0
	v_readfirstlane_b32 s13, v226
	s_add_i32 s12, s13, s12
	s_sext_i32_i16 s66, s12
	s_mul_i32 s12, s12, s19
	s_sub_i32 s3, s3, s12
	s_sext_i32_i16 s3, s3
	s_add_i32 s72, s18, s3
.LBB0_1717:
	s_add_u32 s50, s6, 0x200
	s_addc_u32 s51, s7, 0
	s_ashr_i32 s73, s72, 31
	s_lshl_b64 s[12:13], s[72:73], 19
	s_add_u32 s78, s42, s12
	s_addc_u32 s79, s43, s13
	s_and_b64 s[12:13], s[0:1], exec
	s_cselect_b32 s73, s79, s15
	s_cselect_b32 s93, s78, s14
	s_ashr_i32 s67, s66, 31
	s_lshl_b64 s[12:13], s[66:67], 19
	v_readlane_b32 s18, v255, 15
	v_readlane_b32 s19, v255, 16
	s_add_u32 s74, s18, s12
	s_addc_u32 s75, s19, s13
	s_and_b64 s[12:13], s[0:1], exec
	s_cselect_b32 s67, s75, s7
	s_cselect_b32 s94, s74, s6
	v_lshl_add_u64 v[140:141], s[14:15], 0, v[130:131]
	s_add_i32 s95, s11, 0xc000
	v_lshl_add_u64 v[66:67], v[140:141], 0, s[38:39]
	s_mov_b32 m0, s95
	s_add_i32 s96, s11, 0xe000
	global_load_lds_dwordx4 v[66:67], off
	v_lshl_add_u64 v[66:67], v[140:141], 0, s[40:41]
	s_mov_b32 m0, s96
	s_nop 0
	global_load_lds_dwordx4 v[66:67], off
	s_waitcnt vmcnt(8)
	s_waitcnt lgkmcnt(0)
	s_waitcnt lgkmcnt(0)
	v_mfma_f32_16x16x32_bf16 v[86:89], v[10:13], v[50:53], 0
	v_mfma_f32_16x16x32_bf16 v[90:93], v[14:17], v[54:57], v[86:89]
	s_barrier
	s_setprio 1
	v_mfma_f32_16x16x32_bf16 v[86:89], v[2:5], v[58:61], 0
	v_mfma_f32_16x16x32_bf16 v[66:69], v[2:5], v[34:37], 0
	v_mfma_f32_16x16x32_bf16 v[70:73], v[10:13], v[34:37], 0
	v_mfma_f32_16x16x32_bf16 v[74:77], v[2:5], v[42:45], 0
	v_mfma_f32_16x16x32_bf16 v[78:81], v[10:13], v[42:45], 0
	v_mfma_f32_16x16x32_bf16 v[82:85], v[2:5], v[50:53], 0
	v_mfma_f32_16x16x32_bf16 v[94:97], v[6:9], v[62:65], v[86:89]
	v_mfma_f32_16x16x32_bf16 v[86:89], v[10:13], v[58:61], 0
	v_mfma_f32_16x16x32_bf16 v[66:69], v[6:9], v[38:41], v[66:69]
	v_mfma_f32_16x16x32_bf16 v[70:73], v[14:17], v[38:41], v[70:73]
	v_mfma_f32_16x16x32_bf16 v[74:77], v[6:9], v[46:49], v[74:77]
	v_mfma_f32_16x16x32_bf16 v[78:81], v[14:17], v[46:49], v[78:81]
	v_mfma_f32_16x16x32_bf16 v[82:85], v[6:9], v[54:57], v[82:85]
	v_mfma_f32_16x16x32_bf16 v[106:109], v[14:17], v[62:65], v[86:89]
	s_setprio 0
	s_setprio 1
	v_mfma_f32_16x16x32_bf16 v[86:89], v[18:21], v[34:37], 0
	v_mfma_f32_16x16x32_bf16 v[34:37], v[26:29], v[34:37], 0
	v_mfma_f32_16x16x32_bf16 v[110:113], v[22:25], v[38:41], v[86:89]
	v_mfma_f32_16x16x32_bf16 v[34:37], v[30:33], v[38:41], v[34:37]
	v_mfma_f32_16x16x32_bf16 v[38:41], v[18:21], v[42:45], 0
	v_mfma_f32_16x16x32_bf16 v[42:45], v[26:29], v[42:45], 0
	v_mfma_f32_16x16x32_bf16 v[38:41], v[22:25], v[46:49], v[38:41]
	v_mfma_f32_16x16x32_bf16 v[42:45], v[30:33], v[46:49], v[42:45]
	v_mfma_f32_16x16x32_bf16 v[46:49], v[18:21], v[50:53], 0
	v_mfma_f32_16x16x32_bf16 v[50:53], v[26:29], v[50:53], 0
	v_mfma_f32_16x16x32_bf16 v[46:49], v[22:25], v[54:57], v[46:49]
	v_mfma_f32_16x16x32_bf16 v[50:53], v[30:33], v[54:57], v[50:53]
	v_mfma_f32_16x16x32_bf16 v[54:57], v[18:21], v[58:61], 0
	v_mfma_f32_16x16x32_bf16 v[58:61], v[26:29], v[58:61], 0
	v_mfma_f32_16x16x32_bf16 v[54:57], v[22:25], v[62:65], v[54:57]
	v_mfma_f32_16x16x32_bf16 v[58:61], v[30:33], v[62:65], v[58:61]
	s_setprio 0
	s_barrier
	v_lshl_add_u64 v[184:185], s[6:7], 0, v[132:133]
	s_add_i32 s97, s89, s52
	v_lshl_add_u64 v[150:151], v[184:185], 0, s[46:47]
	s_mov_b32 m0, s97
	s_add_i32 vcc_lo, s97, 0x2000
	ds_read_b128 v[62:65], v147 offset:16384
	ds_read_b128 v[86:89], v147 offset:17408
	ds_read_b128 v[98:101], v147 offset:18432
	ds_read_b128 v[102:105], v147 offset:19456
	ds_read_b128 v[114:117], v147 offset:20480
	ds_read_b128 v[118:121], v147 offset:21504
	ds_read_b128 v[122:125], v147 offset:22528
	ds_read_b128 v[126:129], v147 offset:23552
	global_load_lds_dwordx4 v[150:151], off
	v_lshl_add_u64 v[150:151], v[184:185], 0, s[48:49]
	s_mov_b32 m0, vcc_lo
	s_add_i32 s33, s90, s52
	global_load_lds_dwordx4 v[150:151], off
	v_lshl_add_u64 v[150:151], v[184:185], 0, s[54:55]
	s_mov_b32 m0, s33
	s_add_i32 vcc_hi, s33, 0x2000
	global_load_lds_dwordx4 v[150:151], off
	v_lshl_add_u64 v[150:151], v[184:185], 0, s[56:57]
	s_mov_b32 m0, vcc_hi
	s_nop 0
	global_load_lds_dwordx4 v[150:151], off
	v_lshl_add_u64 v[150:151], v[140:141], 0, s[46:47]
	s_mov_b32 m0, s11
	s_nop 0
	global_load_lds_dwordx4 v[150:151], off
	v_lshl_add_u64 v[150:151], v[140:141], 0, s[48:49]
	s_mov_b32 m0, s77
	s_nop 0
	global_load_lds_dwordx4 v[150:151], off
	s_waitcnt vmcnt(8)
	s_waitcnt lgkmcnt(0)
	s_waitcnt lgkmcnt(0)
	v_mfma_f32_16x16x32_bf16 v[150:153], v[2:5], v[62:65], 0
	v_mfma_f32_16x16x32_bf16 v[160:163], v[2:5], v[98:101], 0
	s_barrier
	s_setprio 1
	v_mfma_f32_16x16x32_bf16 v[168:171], v[2:5], v[114:117], 0
	v_mfma_f32_16x16x32_bf16 v[2:5], v[2:5], v[122:125], 0
	v_mfma_f32_16x16x32_bf16 v[152:155], v[6:9], v[86:89], v[150:153]
	v_mfma_f32_16x16x32_bf16 v[160:163], v[6:9], v[102:105], v[160:163]
	v_mfma_f32_16x16x32_bf16 v[168:171], v[6:9], v[118:121], v[168:171]
	v_mfma_f32_16x16x32_bf16 v[2:5], v[6:9], v[126:129], v[2:5]
	v_mfma_f32_16x16x32_bf16 v[6:9], v[10:13], v[122:125], 0
	v_mfma_f32_16x16x32_bf16 v[156:159], v[10:13], v[62:65], 0
	v_mfma_f32_16x16x32_bf16 v[164:167], v[10:13], v[98:101], 0
	v_mfma_f32_16x16x32_bf16 v[172:175], v[10:13], v[114:117], 0
	v_mfma_f32_16x16x32_bf16 v[10:13], v[14:17], v[126:129], v[6:9]
	v_mfma_f32_16x16x32_bf16 v[156:159], v[14:17], v[86:89], v[156:159]
	v_mfma_f32_16x16x32_bf16 v[164:167], v[14:17], v[102:105], v[164:167]
	v_mfma_f32_16x16x32_bf16 v[172:175], v[14:17], v[118:121], v[172:175]
	s_setprio 0
	s_setprio 1
	v_mfma_f32_16x16x32_bf16 v[6:9], v[18:21], v[62:65], 0
	v_mfma_f32_16x16x32_bf16 v[14:17], v[22:25], v[86:89], v[6:9]
	v_mfma_f32_16x16x32_bf16 v[6:9], v[26:29], v[62:65], 0
	v_mfma_f32_16x16x32_bf16 v[176:179], v[30:33], v[86:89], v[6:9]
	v_mfma_f32_16x16x32_bf16 v[6:9], v[18:21], v[98:101], 0
	v_mfma_f32_16x16x32_bf16 v[180:183], v[22:25], v[102:105], v[6:9]
	v_mfma_f32_16x16x32_bf16 v[6:9], v[26:29], v[98:101], 0
	v_mfma_f32_16x16x32_bf16 v[188:191], v[30:33], v[102:105], v[6:9]
	v_mfma_f32_16x16x32_bf16 v[6:9], v[18:21], v[114:117], 0
	v_mfma_f32_16x16x32_bf16 v[192:195], v[22:25], v[118:121], v[6:9]
	v_mfma_f32_16x16x32_bf16 v[6:9], v[26:29], v[114:117], 0
	v_mfma_f32_16x16x32_bf16 v[196:199], v[30:33], v[118:121], v[6:9]
	v_mfma_f32_16x16x32_bf16 v[6:9], v[18:21], v[122:125], 0
	v_mfma_f32_16x16x32_bf16 v[200:203], v[22:25], v[126:129], v[6:9]
	v_mfma_f32_16x16x32_bf16 v[6:9], v[26:29], v[122:125], 0
	v_mfma_f32_16x16x32_bf16 v[204:207], v[30:33], v[126:129], v[6:9]
	s_setprio 0
	s_barrier
	s_add_i32 s12, 0, 0x18000
	s_add_i32 s3, 0, 0x1c000
	v_add_u32_e32 v149, s12, v144
	v_add_u32_e32 v150, s3, v144
	s_nop 0
	ds_read_b128 v[6:9], v149
	ds_read_b128 v[26:29], v149 offset:1024
	ds_read_b128 v[30:33], v149 offset:2048
	ds_read_b128 v[208:211], v149 offset:3072
	ds_read_b128 v[212:215], v150
	ds_read_b128 v[216:219], v150 offset:1024
	ds_read_b128 v[220:223], v150 offset:2048
	ds_read_b128 v[224:227], v150 offset:3072
	s_mov_b32 m0, s80
	v_lshl_add_u64 v[62:63], v[140:141], 0, s[54:55]
	ds_read_b128 v[18:21], v147 offset:32768
	ds_read_b128 v[22:25], v147 offset:33792
	ds_read_b128 v[228:231], v147 offset:34816
	ds_read_b128 v[232:235], v147 offset:35840
	ds_read_b128 v[236:239], v147 offset:36864
	ds_read_b128 v[240:243], v147 offset:37888
	ds_read_b128 v[244:247], v147 offset:38912
	ds_read_b128 v[248:251], v147 offset:39936
	global_load_lds_dwordx4 v[62:63], off
	v_lshl_add_u64 v[62:63], v[140:141], 0, s[56:57]
	s_mov_b32 m0, s81
	s_nop 0
	global_load_lds_dwordx4 v[62:63], off
	s_waitcnt vmcnt(8)
	s_waitcnt lgkmcnt(0)
	s_waitcnt lgkmcnt(0)
	v_mfma_f32_16x16x32_bf16 v[62:65], v[6:9], v[18:21], v[66:69]
	v_mfma_f32_16x16x32_bf16 v[118:121], v[26:29], v[22:25], v[62:65]
	s_barrier
	s_setprio 1
	v_mfma_f32_16x16x32_bf16 v[62:65], v[30:33], v[18:21], v[70:73]
	v_mfma_f32_16x16x32_bf16 v[114:117], v[208:211], v[22:25], v[62:65]
	v_mfma_f32_16x16x32_bf16 v[62:65], v[6:9], v[228:231], v[74:77]
	v_mfma_f32_16x16x32_bf16 v[102:105], v[26:29], v[232:235], v[62:65]
	v_mfma_f32_16x16x32_bf16 v[62:65], v[30:33], v[228:231], v[78:81]
	v_mfma_f32_16x16x32_bf16 v[98:101], v[208:211], v[232:235], v[62:65]
	v_mfma_f32_16x16x32_bf16 v[62:65], v[6:9], v[236:239], v[82:85]
	v_mfma_f32_16x16x32_bf16 v[86:89], v[26:29], v[240:243], v[62:65]
	v_mfma_f32_16x16x32_bf16 v[62:65], v[30:33], v[236:239], v[90:93]
	v_mfma_f32_16x16x32_bf16 v[82:85], v[208:211], v[240:243], v[62:65]
	v_mfma_f32_16x16x32_bf16 v[62:65], v[6:9], v[244:247], v[94:97]
	v_mfma_f32_16x16x32_bf16 v[70:73], v[26:29], v[248:251], v[62:65]
	v_mfma_f32_16x16x32_bf16 v[62:65], v[30:33], v[244:247], v[106:109]
	v_mfma_f32_16x16x32_bf16 v[62:65], v[208:211], v[248:251], v[62:65]
	s_setprio 0
	s_setprio 1
	v_mfma_f32_16x16x32_bf16 v[66:69], v[212:215], v[18:21], v[110:113]
	v_mfma_f32_16x16x32_bf16 v[18:21], v[220:223], v[18:21], v[34:37]
	v_mfma_f32_16x16x32_bf16 v[122:125], v[224:227], v[22:25], v[18:21]
	v_mfma_f32_16x16x32_bf16 v[18:21], v[212:215], v[228:231], v[38:41]
	v_mfma_f32_16x16x32_bf16 v[110:113], v[216:219], v[232:235], v[18:21]
	v_mfma_f32_16x16x32_bf16 v[18:21], v[220:223], v[228:231], v[42:45]
	v_mfma_f32_16x16x32_bf16 v[106:109], v[224:227], v[232:235], v[18:21]
	v_mfma_f32_16x16x32_bf16 v[18:21], v[212:215], v[236:239], v[46:49]
	v_mfma_f32_16x16x32_bf16 v[94:97], v[216:219], v[240:243], v[18:21]
	v_mfma_f32_16x16x32_bf16 v[18:21], v[220:223], v[236:239], v[50:53]
	v_mfma_f32_16x16x32_bf16 v[90:93], v[224:227], v[240:243], v[18:21]
	v_mfma_f32_16x16x32_bf16 v[18:21], v[212:215], v[244:247], v[54:57]
	v_mfma_f32_16x16x32_bf16 v[78:81], v[216:219], v[248:251], v[18:21]
	v_mfma_f32_16x16x32_bf16 v[18:21], v[220:223], v[244:247], v[58:61]
	v_mfma_f32_16x16x32_bf16 v[126:129], v[216:219], v[22:25], v[66:69]
	v_mfma_f32_16x16x32_bf16 v[74:77], v[224:227], v[248:251], v[18:21]
	s_setprio 0
	s_barrier
	s_add_i32 s12, s12, s52
	s_nop 2
	v_lshl_add_u64 v[18:19], v[184:185], 0, s[58:59]
	s_mov_b32 m0, s12
	s_add_i32 s13, s12, 0x2000
	ds_read_b128 v[42:45], v147 offset:49152
	ds_read_b128 v[46:49], v147 offset:50176
	ds_read_b128 v[228:231], v147 offset:51200
	ds_read_b128 v[232:235], v147 offset:52224
	ds_read_b128 v[236:239], v147 offset:53248
	ds_read_b128 v[240:243], v147 offset:54272
	ds_read_b128 v[244:247], v147 offset:55296
	ds_read_b128 v[248:251], v147 offset:56320
	global_load_lds_dwordx4 v[18:19], off
	v_lshl_add_u64 v[18:19], v[184:185], 0, s[60:61]
	s_mov_b32 m0, s13
	s_add_i32 s3, s3, s52
	global_load_lds_dwordx4 v[18:19], off
	v_lshl_add_u64 v[18:19], v[184:185], 0, s[62:63]
	s_mov_b32 m0, s3
	s_add_i32 s36, s3, 0x2000
	global_load_lds_dwordx4 v[18:19], off
	v_lshl_add_u64 v[18:19], v[184:185], 0, s[64:65]
	s_mov_b32 m0, s36
	s_nop 0
	global_load_lds_dwordx4 v[18:19], off
	v_lshl_add_u64 v[18:19], v[140:141], 0, s[58:59]
	s_mov_b32 m0, s86
	s_nop 0
	global_load_lds_dwordx4 v[18:19], off
	v_lshl_add_u64 v[18:19], v[140:141], 0, s[60:61]
	s_mov_b32 m0, s87
	s_nop 0
	global_load_lds_dwordx4 v[18:19], off
	s_waitcnt vmcnt(8)
	s_waitcnt lgkmcnt(0)
	s_waitcnt lgkmcnt(0)
	v_mfma_f32_16x16x32_bf16 v[18:21], v[6:9], v[42:45], v[152:155]
	v_mfma_f32_16x16x32_bf16 v[54:57], v[26:29], v[46:49], v[18:21]
	s_barrier
	s_setprio 1
	v_mfma_f32_16x16x32_bf16 v[18:21], v[30:33], v[42:45], v[156:159]
	v_mfma_f32_16x16x32_bf16 v[50:53], v[208:211], v[46:49], v[18:21]
	v_mfma_f32_16x16x32_bf16 v[18:21], v[6:9], v[228:231], v[160:163]
	v_mfma_f32_16x16x32_bf16 v[38:41], v[26:29], v[232:235], v[18:21]
	v_mfma_f32_16x16x32_bf16 v[18:21], v[30:33], v[228:231], v[164:167]
	v_mfma_f32_16x16x32_bf16 v[34:37], v[208:211], v[232:235], v[18:21]
	v_mfma_f32_16x16x32_bf16 v[18:21], v[6:9], v[236:239], v[168:171]
	v_mfma_f32_16x16x32_bf16 v[2:5], v[6:9], v[244:247], v[2:5]
	v_mfma_f32_16x16x32_bf16 v[22:25], v[26:29], v[240:243], v[18:21]
	v_mfma_f32_16x16x32_bf16 v[18:21], v[30:33], v[236:239], v[172:175]
	v_mfma_f32_16x16x32_bf16 v[6:9], v[26:29], v[248:251], v[2:5]
	v_mfma_f32_16x16x32_bf16 v[2:5], v[30:33], v[244:247], v[10:13]
	v_mfma_f32_16x16x32_bf16 v[18:21], v[208:211], v[240:243], v[18:21]
	v_mfma_f32_16x16x32_bf16 v[2:5], v[208:211], v[248:251], v[2:5]
	s_setprio 0
	s_setprio 1
	v_mfma_f32_16x16x32_bf16 v[10:13], v[212:215], v[42:45], v[14:17]
	v_mfma_f32_16x16x32_bf16 v[66:69], v[216:219], v[46:49], v[10:13]
	v_mfma_f32_16x16x32_bf16 v[10:13], v[220:223], v[42:45], v[176:179]
	v_mfma_f32_16x16x32_bf16 v[58:61], v[224:227], v[46:49], v[10:13]
	v_mfma_f32_16x16x32_bf16 v[10:13], v[212:215], v[228:231], v[180:183]
	v_mfma_f32_16x16x32_bf16 v[46:49], v[216:219], v[232:235], v[10:13]
	v_mfma_f32_16x16x32_bf16 v[10:13], v[220:223], v[228:231], v[188:191]
	v_mfma_f32_16x16x32_bf16 v[42:45], v[224:227], v[232:235], v[10:13]
	v_mfma_f32_16x16x32_bf16 v[10:13], v[212:215], v[236:239], v[192:195]
	v_mfma_f32_16x16x32_bf16 v[30:33], v[216:219], v[240:243], v[10:13]
	v_mfma_f32_16x16x32_bf16 v[10:13], v[220:223], v[236:239], v[196:199]
	v_mfma_f32_16x16x32_bf16 v[26:29], v[224:227], v[240:243], v[10:13]
	v_mfma_f32_16x16x32_bf16 v[10:13], v[212:215], v[244:247], v[200:203]
	v_mfma_f32_16x16x32_bf16 v[14:17], v[216:219], v[248:251], v[10:13]
	v_mfma_f32_16x16x32_bf16 v[10:13], v[220:223], v[244:247], v[204:207]
	v_mfma_f32_16x16x32_bf16 v[10:13], v[224:227], v[248:251], v[10:13]
	s_setprio 0
	s_barrier
	v_lshl_add_u64 v[140:141], s[14:15], 0, v[134:135]
	s_mov_b32 s37, 0
	s_mov_b64 s[6:7], 0
